# up phase: the G_5 guard load is issued at phase start (wait moved to its first consumer); the first epilogue re-loads only if that value was incomplete
# baseline (speedup 1.0000x reference)
.Lxb5_end:
.LBB0_1060:
	s_mov_b32 s100, 0
	s_or_b64 exec, exec, s[0:1]
	v_readlane_b32 s60, v252, 11
	v_readlane_b32 s61, v252, 12
	v_mov_b32_e32 v251, 0
	s_add_u32 s60, s60, 0x10800
	s_addc_u32 s61, s61, 0
	global_load_dword v250, v251, s[60:61] sc1
	v_readlane_b32 s8, v252, 0
	v_readlane_b32 s9, v252, 1
	v_readlane_b32 s10, v252, 2
	v_readlane_b32 s11, v252, 3
	v_readlane_b32 s12, v252, 4
	v_readlane_b32 s13, v252, 5
	v_readlane_b32 s14, v252, 6
	v_readlane_b32 s15, v252, 7
	s_mov_b64 s[8:9], s[12:13]
	s_mov_b64 s[10:11], s[14:15]
	s_add_u32 s8, s10, 0x4160000
	s_addc_u32 s9, s11, 0
	v_mov_b32_e32 v9, v176
	s_waitcnt lgkmcnt(0)
	s_barrier
	s_cmpk_gt_i32 s72, 0x3ff
	v_readfirstlane_b32 s7, v9
	s_cbranch_scc1 .LBB0_1086
	s_ashr_i32 s2, s72, 31
	s_lshr_b32 s0, s2, 29
	s_add_i32 s3, s72, s0
	s_and_b32 s0, s3, -8
	s_sub_i32 s10, s72, s0
	s_cmp_gt_i32 s10, -1
	s_cbranch_scc0 .LBB0_1063
	s_lshl_b32 s6, s10, 7
	s_cbranch_execz .LBB0_1064
	s_branch .LBB0_1065

.LBB0_1082:
	s_cmp_lg_u32 s100, 0
	s_cbranch_scc1 .Lgd5_skip
	v_cmp_le_u32_e32 vcc, s86, v250
	s_cbranch_vccnz .Lgd5_pre
	v_readlane_b32 s60, v252, 11
	v_readlane_b32 s61, v252, 12
	v_mov_b32_e32 v170, 0
	s_mov_b32 s62, 0
	s_add_u32 s60, s60, 0x10800
	s_addc_u32 s61, s61, 0

.Lgd5_ok:
.Lgd5_pre:
	s_mov_b32 s100, 1
